# XCDs with blockIdx bit 2 set enter P5 ~35us late (XCD-local barriers keep the skew through P5/P7/P8) so the epilogue HBM bursts of the two chip halves interleave
# speedup vs baseline: 1.0007x; 1.0007x over previous
; __global__ void __launch_bounds__(NTHR, 2) fwd_megakernel(Args a) {
;     ...
;         pg8::Gemm g{H, WoT, M, DM, DM}; pg8::StaticOrderW<4> S; S.init(M, DM, G, blk);
;         pg8::EpiRes3 E{x, out, mod, g2, H2, part};
;         pg8::gemm_phase<pg8::EpiRes3, pg8::StaticOrderW<4>, true, true>(lds, g, S, E);
.LBB0_663:
	s_or_b64 exec, exec, s[2:3]
	v_readfirstlane_b32 s98, v237
	s_and_b32 s98, s98, 4
	s_cmp_eq_u32 s98, 0
	s_cbranch_scc1 .Lskew_skip
	s_sleep 127
	s_sleep 127
	s_sleep 127
	s_sleep 127
	s_sleep 127
	s_sleep 127
	s_sleep 127
	s_sleep 127
	s_sleep 127
	s_sleep 127
